# v38 + attention loop: K-fragment ds_read moved behind the three exp fillers after each QK MFMA (MFMA-first gap filling)
# speedup vs baseline: 1.0059x; 1.0059x over previous
.Latt_loop:
	s_add_i32 s13, s12, 1
	s_cmp_eq_u32 s12, 2
	s_cselect_b32 s12, 0, s13
	s_mul_i32 s15, s12, 0x4800
	s_mul_i32 s16, s12, 0x6000
	s_add_i32 s16, s16, 0xd800
	s_add_i32 s17, s14, 2
	s_min_u32 s17, s17, s11
	s_lshl_b32 s64, s17, 17
	s_add_u32 s18, s64, s83
	s_mov_b32 s19, 0
	s_add_i32 s14, s14, 1
	v_mov_b32_e32 v250, v251
	v_add3_u32 v251, s15, v236, v210
	v_mov_b32_e32 v252, v215
	v_add_u32_e32 v215, s16, v232
	s_waitcnt lgkmcnt(5)
	v_mfma_f32_32x32x16_bf16 v[98:113], v[238:241], v[134:137], 0
	v_exp_f32_e32 v66, v66
	v_exp_f32_e32 v67, v67
	v_exp_f32_e32 v68, v68
	ds_read_b128 v[238:241], v250 offset:4672
	v_mfma_f32_32x32x16_bf16 v[34:49], v[182:185], v[118:121], v[34:49]
	v_exp_f32_e32 v69, v69
	v_exp_f32_e32 v70, v70
	v_exp_f32_e32 v71, v71
	v_mfma_f32_32x32x16_bf16 v[50:65], v[186:189], v[118:121], v[50:65]
	ds_read_b64_tr_b16 v[182:183], v252 offset:3072
	ds_read_b64_tr_b16 v[184:185], v252 offset:4608
	ds_read_b64_tr_b16 v[186:187], v252 offset:3136
	ds_read_b64_tr_b16 v[188:189], v252 offset:4672
	v_exp_f32_e32 v72, v72
	v_exp_f32_e32 v73, v73
	v_cvt_pk_bf16_f32 v66, v66, v67
	v_cvt_pk_bf16_f32 v67, v68, v69
	v_mfma_f32_16x16x32_bf16 v[170:173], v[130:133], v[118:121], v[170:173]
	v_cvt_pk_bf16_f32 v68, v70, v71
	v_cvt_pk_bf16_f32 v69, v72, v73
	s_waitcnt vmcnt(0)
	v_add_u32_e32 v246, s15, v204
	v_add_u32_e32 v247, s16, v231
	ds_write_b128 v246, v[158:161]
	ds_write_b128 v246, v[162:165] offset:9216
	ds_write_b128 v247, v[150:153]
	ds_write_b128 v247, v[154:157] offset:12288
	s_add_u32 s18, s100, s64
	s_addc_u32 s19, s101, 0
	global_load_dwordx4 v[158:161], v248, s[18:19]
	global_load_dwordx4 v[162:165], v249, s[18:19]
	s_add_u32 s18, s18, 0x1040000
	s_addc_u32 s19, s19, 0
	global_load_dwordx4 v[150:153], v248, s[18:19]
	global_load_dwordx4 v[154:157], v249, s[18:19]
	s_waitcnt lgkmcnt(9)
	v_mfma_f32_32x32x16_bf16 v[98:113], v[242:245], v[138:141], v[98:113]
	v_exp_f32_e32 v82, v82
	v_exp_f32_e32 v83, v83
	v_exp_f32_e32 v84, v84
	ds_read_b128 v[242:245], v250 offset:4704
	v_mfma_f32_32x32x16_bf16 v[2:17], v[174:177], v[66:69], v[2:17]
	v_exp_f32_e32 v85, v85
	v_exp_f32_e32 v86, v86
	v_exp_f32_e32 v87, v87
	v_mfma_f32_32x32x16_bf16 v[18:33], v[178:181], v[66:69], v[18:33]
	v_exp_f32_e32 v88, v88
	v_exp_f32_e32 v89, v89
	v_cvt_pk_bf16_f32 v82, v82, v83
	v_cvt_pk_bf16_f32 v83, v84, v85
	v_mfma_f32_16x16x32_bf16 v[166:169], v[130:133], v[66:69], v[166:169]
	v_cvt_pk_bf16_f32 v84, v86, v87
	v_cvt_pk_bf16_f32 v85, v88, v89
	s_waitcnt lgkmcnt(9)
	v_mfma_f32_32x32x16_bf16 v[114:129], v[238:241], v[142:145], 0
	v_exp_f32_e32 v74, v74
	v_exp_f32_e32 v75, v75
	v_exp_f32_e32 v76, v76
	ds_read_b128 v[238:241], v250 offset:9216
	v_mfma_f32_32x32x16_bf16 v[34:49], v[174:177], v[82:85], v[34:49]
	v_exp_f32_e32 v77, v77
	v_exp_f32_e32 v78, v78
	v_exp_f32_e32 v79, v79
	v_mfma_f32_32x32x16_bf16 v[50:65], v[178:181], v[82:85], v[50:65]
	ds_read_b64_tr_b16 v[174:175], v252 offset:6144
	ds_read_b64_tr_b16 v[176:177], v252 offset:7680
	ds_read_b64_tr_b16 v[178:179], v252 offset:6208
	ds_read_b64_tr_b16 v[180:181], v252 offset:7744
	v_exp_f32_e32 v80, v80
	v_exp_f32_e32 v81, v81
	v_cvt_pk_bf16_f32 v70, v74, v75
	v_cvt_pk_bf16_f32 v71, v76, v77
	v_mfma_f32_16x16x32_bf16 v[170:173], v[130:133], v[82:85], v[170:173]
	v_cvt_pk_bf16_f32 v72, v78, v79
	v_cvt_pk_bf16_f32 v73, v80, v81
	s_waitcnt lgkmcnt(5)
	v_mfma_f32_32x32x16_bf16 v[114:129], v[242:245], v[146:149], v[114:129]
	v_exp_f32_e32 v90, v90
	v_exp_f32_e32 v91, v91
	v_exp_f32_e32 v92, v92
	ds_read_b128 v[242:245], v250 offset:9248
	v_mfma_f32_32x32x16_bf16 v[2:17], v[182:185], v[70:73], v[2:17]
	v_exp_f32_e32 v93, v93
	v_exp_f32_e32 v94, v94
	v_exp_f32_e32 v95, v95
	v_mfma_f32_32x32x16_bf16 v[18:33], v[186:189], v[70:73], v[18:33]
	v_exp_f32_e32 v96, v96
	v_exp_f32_e32 v97, v97
	v_cvt_pk_bf16_f32 v86, v90, v91
	v_cvt_pk_bf16_f32 v87, v92, v93
	v_mfma_f32_16x16x32_bf16 v[166:169], v[130:133], v[70:73], v[166:169]
	v_cvt_pk_bf16_f32 v88, v94, v95
	v_cvt_pk_bf16_f32 v89, v96, v97
	s_waitcnt lgkmcnt(5)
	v_mfma_f32_32x32x16_bf16 v[66:81], v[238:241], v[134:137], 0
	v_exp_f32_e32 v98, v98
	v_exp_f32_e32 v99, v99
	v_exp_f32_e32 v100, v100
	ds_read_b128 v[238:241], v250 offset:9280
	v_mfma_f32_32x32x16_bf16 v[34:49], v[182:185], v[86:89], v[34:49]
	v_exp_f32_e32 v101, v101
	v_exp_f32_e32 v102, v102
	v_exp_f32_e32 v103, v103
	v_mfma_f32_32x32x16_bf16 v[50:65], v[186:189], v[86:89], v[50:65]
	ds_read_b64_tr_b16 v[182:183], v252 offset:9216
	ds_read_b64_tr_b16 v[184:185], v252 offset:10752
	ds_read_b64_tr_b16 v[186:187], v252 offset:9280
	ds_read_b64_tr_b16 v[188:189], v252 offset:10816
	v_exp_f32_e32 v104, v104
	v_exp_f32_e32 v105, v105
	v_cvt_pk_bf16_f32 v98, v98, v99
	v_cvt_pk_bf16_f32 v99, v100, v101
	v_mfma_f32_16x16x32_bf16 v[170:173], v[130:133], v[86:89], v[170:173]
	v_cvt_pk_bf16_f32 v100, v102, v103
	v_cvt_pk_bf16_f32 v101, v104, v105
	s_waitcnt lgkmcnt(5)
	v_mfma_f32_32x32x16_bf16 v[66:81], v[242:245], v[138:141], v[66:81]
	v_exp_f32_e32 v114, v114
	v_exp_f32_e32 v115, v115
	v_exp_f32_e32 v116, v116
	ds_read_b128 v[242:245], v250 offset:9312
	v_mfma_f32_32x32x16_bf16 v[2:17], v[174:177], v[98:101], v[2:17]
	v_exp_f32_e32 v117, v117
	v_exp_f32_e32 v118, v118
	v_exp_f32_e32 v119, v119
	v_mfma_f32_32x32x16_bf16 v[18:33], v[178:181], v[98:101], v[18:33]
	v_exp_f32_e32 v120, v120
	v_exp_f32_e32 v121, v121
	v_cvt_pk_bf16_f32 v114, v114, v115
	v_cvt_pk_bf16_f32 v115, v116, v117
	v_mfma_f32_16x16x32_bf16 v[166:169], v[130:133], v[98:101], v[166:169]
	v_cvt_pk_bf16_f32 v116, v118, v119
	v_cvt_pk_bf16_f32 v117, v120, v121
	s_waitcnt lgkmcnt(5)
	v_mfma_f32_32x32x16_bf16 v[82:97], v[238:241], v[142:145], 0
	v_exp_f32_e32 v106, v106
	v_exp_f32_e32 v107, v107
	v_exp_f32_e32 v108, v108
	ds_read_b128 v[238:241], v250 offset:13824
	v_mfma_f32_32x32x16_bf16 v[34:49], v[174:177], v[114:117], v[34:49]
	v_exp_f32_e32 v109, v109
	v_exp_f32_e32 v110, v110
	v_exp_f32_e32 v111, v111
	v_mfma_f32_32x32x16_bf16 v[50:65], v[178:181], v[114:117], v[50:65]
	ds_read_b64_tr_b16 v[174:175], v252 offset:12288
	ds_read_b64_tr_b16 v[176:177], v252 offset:13824
	ds_read_b64_tr_b16 v[178:179], v252 offset:12352
	ds_read_b64_tr_b16 v[180:181], v252 offset:13888
	v_exp_f32_e32 v112, v112
	v_exp_f32_e32 v113, v113
	v_cvt_pk_bf16_f32 v102, v106, v107
	v_cvt_pk_bf16_f32 v103, v108, v109
	v_mfma_f32_16x16x32_bf16 v[170:173], v[130:133], v[114:117], v[170:173]
	v_cvt_pk_bf16_f32 v104, v110, v111
	v_cvt_pk_bf16_f32 v105, v112, v113
	s_waitcnt lgkmcnt(5)
	v_mfma_f32_32x32x16_bf16 v[82:97], v[242:245], v[146:149], v[82:97]
	v_exp_f32_e32 v122, v122
	v_exp_f32_e32 v123, v123
	v_exp_f32_e32 v124, v124
	ds_read_b128 v[242:245], v250 offset:13856
	v_mfma_f32_32x32x16_bf16 v[2:17], v[182:185], v[102:105], v[2:17]
	v_exp_f32_e32 v125, v125
	v_exp_f32_e32 v126, v126
	v_exp_f32_e32 v127, v127
	v_mfma_f32_32x32x16_bf16 v[18:33], v[186:189], v[102:105], v[18:33]
	v_exp_f32_e32 v128, v128
	v_exp_f32_e32 v129, v129
	v_cvt_pk_bf16_f32 v118, v122, v123
	v_cvt_pk_bf16_f32 v119, v124, v125
	v_mfma_f32_16x16x32_bf16 v[166:169], v[130:133], v[102:105], v[166:169]
	v_cvt_pk_bf16_f32 v120, v126, v127
	v_cvt_pk_bf16_f32 v121, v128, v129
	s_waitcnt lgkmcnt(5)
	v_mfma_f32_32x32x16_bf16 v[98:113], v[238:241], v[134:137], 0
	v_exp_f32_e32 v66, v66
	v_exp_f32_e32 v67, v67
	v_exp_f32_e32 v68, v68
	ds_read_b128 v[238:241], v250 offset:13888
	v_mfma_f32_32x32x16_bf16 v[34:49], v[182:185], v[118:121], v[34:49]
	v_exp_f32_e32 v69, v69
	v_exp_f32_e32 v70, v70
	v_exp_f32_e32 v71, v71
	v_mfma_f32_32x32x16_bf16 v[50:65], v[186:189], v[118:121], v[50:65]
	ds_read_b64_tr_b16 v[182:183], v252 offset:15360
	ds_read_b64_tr_b16 v[184:185], v252 offset:16896
	ds_read_b64_tr_b16 v[186:187], v252 offset:15424
	ds_read_b64_tr_b16 v[188:189], v252 offset:16960
	v_exp_f32_e32 v72, v72
	v_exp_f32_e32 v73, v73
	v_cvt_pk_bf16_f32 v66, v66, v67
	v_cvt_pk_bf16_f32 v67, v68, v69
	v_mfma_f32_16x16x32_bf16 v[170:173], v[130:133], v[118:121], v[170:173]
	v_cvt_pk_bf16_f32 v68, v70, v71
	v_cvt_pk_bf16_f32 v69, v72, v73
	s_waitcnt lgkmcnt(5)
	v_mfma_f32_32x32x16_bf16 v[98:113], v[242:245], v[138:141], v[98:113]
	v_exp_f32_e32 v82, v82
	v_exp_f32_e32 v83, v83
	v_exp_f32_e32 v84, v84
	ds_read_b128 v[242:245], v250 offset:13920
	v_mfma_f32_32x32x16_bf16 v[2:17], v[174:177], v[66:69], v[2:17]
	v_exp_f32_e32 v85, v85
	v_exp_f32_e32 v86, v86
	v_exp_f32_e32 v87, v87
	v_mfma_f32_32x32x16_bf16 v[18:33], v[178:181], v[66:69], v[18:33]
	v_exp_f32_e32 v88, v88
	v_exp_f32_e32 v89, v89
	v_cvt_pk_bf16_f32 v82, v82, v83
	v_cvt_pk_bf16_f32 v83, v84, v85
	v_mfma_f32_16x16x32_bf16 v[166:169], v[130:133], v[66:69], v[166:169]
	v_cvt_pk_bf16_f32 v84, v86, v87
	v_cvt_pk_bf16_f32 v85, v88, v89
	s_barrier
	s_waitcnt lgkmcnt(5)
	v_mfma_f32_32x32x16_bf16 v[114:129], v[238:241], v[142:145], 0
	v_exp_f32_e32 v74, v74
	v_exp_f32_e32 v75, v75
	v_exp_f32_e32 v76, v76
	ds_read_b128 v[238:241], v251
	v_mfma_f32_32x32x16_bf16 v[34:49], v[174:177], v[82:85], v[34:49]
	v_exp_f32_e32 v77, v77
	v_exp_f32_e32 v78, v78
	v_exp_f32_e32 v79, v79
	v_mfma_f32_32x32x16_bf16 v[50:65], v[178:181], v[82:85], v[50:65]
	ds_read_b64_tr_b16 v[174:175], v252 offset:18432
	ds_read_b64_tr_b16 v[176:177], v252 offset:19968
	ds_read_b64_tr_b16 v[178:179], v252 offset:18496
	ds_read_b64_tr_b16 v[180:181], v252 offset:20032
	v_exp_f32_e32 v80, v80
	v_exp_f32_e32 v81, v81
	v_cvt_pk_bf16_f32 v70, v74, v75
	v_cvt_pk_bf16_f32 v71, v76, v77
	v_mfma_f32_16x16x32_bf16 v[170:173], v[130:133], v[82:85], v[170:173]
	v_cvt_pk_bf16_f32 v72, v78, v79
	v_cvt_pk_bf16_f32 v73, v80, v81
	s_waitcnt lgkmcnt(5)
	v_mfma_f32_32x32x16_bf16 v[114:129], v[242:245], v[146:149], v[114:129]
	v_exp_f32_e32 v90, v90
	v_exp_f32_e32 v91, v91
	v_exp_f32_e32 v92, v92
	ds_read_b128 v[242:245], v251 offset:32
	v_mfma_f32_32x32x16_bf16 v[2:17], v[182:185], v[70:73], v[2:17]
	v_exp_f32_e32 v93, v93
	v_exp_f32_e32 v94, v94
	v_exp_f32_e32 v95, v95
	v_mfma_f32_32x32x16_bf16 v[18:33], v[186:189], v[70:73], v[18:33]
	v_exp_f32_e32 v96, v96
	v_exp_f32_e32 v97, v97
	v_cvt_pk_bf16_f32 v86, v90, v91
	v_cvt_pk_bf16_f32 v87, v92, v93
	v_mfma_f32_16x16x32_bf16 v[166:169], v[130:133], v[70:73], v[166:169]
	v_cvt_pk_bf16_f32 v88, v94, v95
	v_cvt_pk_bf16_f32 v89, v96, v97
	s_waitcnt lgkmcnt(5)
	v_mfma_f32_32x32x16_bf16 v[66:81], v[238:241], v[134:137], 0
	v_exp_f32_e32 v98, v98
	v_exp_f32_e32 v99, v99
	v_exp_f32_e32 v100, v100
	ds_read_b128 v[238:241], v251 offset:64
	v_mfma_f32_32x32x16_bf16 v[34:49], v[182:185], v[86:89], v[34:49]
	v_exp_f32_e32 v101, v101
	v_exp_f32_e32 v102, v102
	v_exp_f32_e32 v103, v103
	v_mfma_f32_32x32x16_bf16 v[50:65], v[186:189], v[86:89], v[50:65]
	ds_read_b64_tr_b16 v[182:183], v252 offset:21504
	ds_read_b64_tr_b16 v[184:185], v252 offset:23040
	ds_read_b64_tr_b16 v[186:187], v252 offset:21568
	ds_read_b64_tr_b16 v[188:189], v252 offset:23104
	v_exp_f32_e32 v104, v104
	v_exp_f32_e32 v105, v105
	v_cvt_pk_bf16_f32 v98, v98, v99
	v_cvt_pk_bf16_f32 v99, v100, v101
	v_mfma_f32_16x16x32_bf16 v[170:173], v[130:133], v[86:89], v[170:173]
	v_cvt_pk_bf16_f32 v100, v102, v103
	v_cvt_pk_bf16_f32 v101, v104, v105
	s_waitcnt lgkmcnt(5)
	v_mfma_f32_32x32x16_bf16 v[66:81], v[242:245], v[138:141], v[66:81]
	v_exp_f32_e32 v114, v114
	v_exp_f32_e32 v115, v115
	v_exp_f32_e32 v116, v116
	ds_read_b128 v[242:245], v251 offset:96
	v_mfma_f32_32x32x16_bf16 v[2:17], v[174:177], v[98:101], v[2:17]
	v_exp_f32_e32 v117, v117
	v_exp_f32_e32 v118, v118
	v_exp_f32_e32 v119, v119
	v_mfma_f32_32x32x16_bf16 v[18:33], v[178:181], v[98:101], v[18:33]
	v_exp_f32_e32 v120, v120
	v_exp_f32_e32 v121, v121
	v_cvt_pk_bf16_f32 v114, v114, v115
	v_cvt_pk_bf16_f32 v115, v116, v117
	v_mfma_f32_16x16x32_bf16 v[166:169], v[130:133], v[98:101], v[166:169]
	v_cvt_pk_bf16_f32 v116, v118, v119
	v_cvt_pk_bf16_f32 v117, v120, v121
	s_waitcnt lgkmcnt(5)
	v_mfma_f32_32x32x16_bf16 v[82:97], v[238:241], v[142:145], 0
	v_exp_f32_e32 v106, v106
	v_exp_f32_e32 v107, v107
	v_exp_f32_e32 v108, v108
	ds_read_b128 v[238:241], v251 offset:4608
	v_mfma_f32_32x32x16_bf16 v[34:49], v[174:177], v[114:117], v[34:49]
	v_exp_f32_e32 v109, v109
	v_exp_f32_e32 v110, v110
	v_exp_f32_e32 v111, v111
	v_mfma_f32_32x32x16_bf16 v[50:65], v[178:181], v[114:117], v[50:65]
	ds_read_b64_tr_b16 v[174:175], v215
	ds_read_b64_tr_b16 v[176:177], v215 offset:1536
	ds_read_b64_tr_b16 v[178:179], v215 offset:64
	ds_read_b64_tr_b16 v[180:181], v215 offset:1600
	v_exp_f32_e32 v112, v112
	v_exp_f32_e32 v113, v113
	v_cvt_pk_bf16_f32 v102, v106, v107
	v_cvt_pk_bf16_f32 v103, v108, v109
	v_mfma_f32_16x16x32_bf16 v[170:173], v[130:133], v[114:117], v[170:173]
	v_cvt_pk_bf16_f32 v104, v110, v111
	v_cvt_pk_bf16_f32 v105, v112, v113
	s_waitcnt lgkmcnt(5)
	v_mfma_f32_32x32x16_bf16 v[82:97], v[242:245], v[146:149], v[82:97]
	v_exp_f32_e32 v122, v122
	v_exp_f32_e32 v123, v123
	v_exp_f32_e32 v124, v124
	ds_read_b128 v[242:245], v251 offset:4640
	v_mfma_f32_32x32x16_bf16 v[2:17], v[182:185], v[102:105], v[2:17]
	v_exp_f32_e32 v125, v125
	v_exp_f32_e32 v126, v126
	v_exp_f32_e32 v127, v127
	v_mfma_f32_32x32x16_bf16 v[18:33], v[186:189], v[102:105], v[18:33]
	v_exp_f32_e32 v128, v128
	v_exp_f32_e32 v129, v129
	v_cvt_pk_bf16_f32 v118, v122, v123
	v_cvt_pk_bf16_f32 v119, v124, v125
	v_mfma_f32_16x16x32_bf16 v[166:169], v[130:133], v[102:105], v[166:169]
	v_cvt_pk_bf16_f32 v120, v126, v127
	v_cvt_pk_bf16_f32 v121, v128, v129
	s_cmp_lg_u32 s14, s10
	s_cbranch_scc1 .Latt_loop
	s_waitcnt lgkmcnt(0)
	s_nop 1
	v_mfma_f32_16x16x32_bf16 v[170:173], v[130:133], v[118:121], v[170:173]
	v_mfma_f32_32x32x16_bf16 v[34:49], v[182:185], v[118:121], v[34:49]
	v_mfma_f32_32x32x16_bf16 v[50:65], v[186:189], v[118:121], v[50:65]
	s_nop 11
	global_load_dwordx4 v[98:101], v[212:213], off offset:32
	global_load_dwordx4 v[102:105], v[212:213], off offset:64
	global_load_dwordx4 v[106:109], v[212:213], off offset:96
	global_load_dwordx4 v[110:113], v[212:213], off offset:128
	global_load_dwordx4 v[114:117], v[212:213], off offset:160
	global_load_dwordx4 v[122:125], v[212:213], off offset:192
	global_load_dwordx4 v[126:129], v[212:213], off offset:224
	ds_bpermute_b32 v66, v237, v166
	s_nop 3
	ds_bpermute_b32 v67, v237, v170
	s_lshl_b32 s64, s9, 1
	v_mov_b32_e32 v215, v191
	s_mov_b32 s2, 0xf226000
	s_waitcnt lgkmcnt(1)
	v_div_scale_f32 v68, s[10:11], v66, v66, 1.0
	v_rcp_f32_e32 v69, v68
	s_add_i32 s8, s8, 1
	s_cmp_eq_u32 s8, s7
	v_fma_f32 v70, -v68, v69, 1.0
	v_fmac_f32_e32 v69, v70, v69
	v_div_scale_f32 v70, vcc, 1.0, v66, 1.0
	v_mul_f32_e32 v71, v70, v69
	v_fma_f32 v72, -v68, v71, v70
	v_fmac_f32_e32 v71, v72, v69
	v_fma_f32 v68, -v68, v71, v70
	v_div_fmas_f32 v68, v68, v69, v71
	v_div_fixup_f32 v66, v68, v66, 1.0
	s_waitcnt lgkmcnt(0)
	v_div_scale_f32 v68, s[10:11], v67, v67, v230
	v_rcp_f32_e32 v69, v68
	s_mov_b64 s[10:11], 0xf226400
	v_fma_f32 v70, -v68, v69, 1.0
	v_fmac_f32_e32 v69, v70, v69
	v_div_scale_f32 v70, vcc, v230, v67, v230
	v_mul_f32_e32 v71, v70, v69
	v_fma_f32 v72, -v68, v71, v70
	v_fmac_f32_e32 v71, v72, v69
	v_fma_f32 v68, -v68, v71, v70
	v_div_fmas_f32 v68, v68, v69, v71
	v_div_fixup_f32 v68, v68, v67, v230
	v_pk_mul_f32 v[62:63], v[62:63], v[68:69] op_sel_hi:[1,0]
	v_pk_mul_f32 v[34:35], v[34:35], v[68:69] op_sel_hi:[1,0]
	v_pk_fma_f32 v[30:31], v[30:31], v[66:67], v[62:63] op_sel_hi:[1,0,1] neg_lo:[0,0,1] neg_hi:[0,0,1]
	v_pk_mul_f32 v[62:63], v[64:65], v[68:69] op_sel_hi:[1,0]
	v_pk_mul_f32 v[36:37], v[36:37], v[68:69] op_sel_hi:[1,0]
	v_pk_fma_f32 v[32:33], v[32:33], v[66:67], v[62:63] op_sel_hi:[1,0,1] neg_lo:[0,0,1] neg_hi:[0,0,1]
	v_lshlrev_b64 v[62:63], 11, v[216:217]
	v_lshl_add_u64 v[62:63], s[54:55], 0, v[62:63]
	v_lshl_add_u64 v[74:75], v[62:63], 0, s[64:65]
	global_load_dwordx4 v[62:65], v[212:213], off
	v_pk_fma_f32 v[34:35], v[2:3], v[66:67], v[34:35] op_sel_hi:[1,0,1] neg_lo:[0,0,1] neg_hi:[0,0,1]
	v_pk_fma_f32 v[4:5], v[4:5], v[66:67], v[36:37] op_sel_hi:[1,0,1] neg_lo:[0,0,1] neg_hi:[0,0,1]
	v_pk_mul_f32 v[76:77], v[34:35], v[34:35]
	v_pk_mul_f32 v[40:41], v[40:41], v[68:69] op_sel_hi:[1,0]
	v_pk_mul_f32 v[38:39], v[38:39], v[68:69] op_sel_hi:[1,0]
	v_pk_mul_f32 v[44:45], v[44:45], v[68:69] op_sel_hi:[1,0]
	v_pk_mul_f32 v[42:43], v[42:43], v[68:69] op_sel_hi:[1,0]
	v_pk_mul_f32 v[48:49], v[48:49], v[68:69] op_sel_hi:[1,0]
	v_pk_mul_f32 v[46:47], v[46:47], v[68:69] op_sel_hi:[1,0]
	v_pk_mul_f32 v[52:53], v[52:53], v[68:69] op_sel_hi:[1,0]
	v_pk_mul_f32 v[50:51], v[50:51], v[68:69] op_sel_hi:[1,0]
	v_pk_mul_f32 v[56:57], v[56:57], v[68:69] op_sel_hi:[1,0]
	v_pk_mul_f32 v[54:55], v[54:55], v[68:69] op_sel_hi:[1,0]
	v_pk_mul_f32 v[60:61], v[60:61], v[68:69] op_sel_hi:[1,0]
	v_pk_mul_f32 v[58:59], v[58:59], v[68:69] op_sel_hi:[1,0]
	v_pk_mul_f32 v[36:37], v[4:5], v[4:5]
	v_pk_fma_f32 v[8:9], v[8:9], v[66:67], v[40:41] op_sel_hi:[1,0,1] neg_lo:[0,0,1] neg_hi:[0,0,1]
	v_pk_fma_f32 v[38:39], v[6:7], v[66:67], v[38:39] op_sel_hi:[1,0,1] neg_lo:[0,0,1] neg_hi:[0,0,1]
	v_pk_fma_f32 v[12:13], v[12:13], v[66:67], v[44:45] op_sel_hi:[1,0,1] neg_lo:[0,0,1] neg_hi:[0,0,1]
	v_pk_fma_f32 v[10:11], v[10:11], v[66:67], v[42:43] op_sel_hi:[1,0,1] neg_lo:[0,0,1] neg_hi:[0,0,1]
	v_pk_fma_f32 v[16:17], v[16:17], v[66:67], v[48:49] op_sel_hi:[1,0,1] neg_lo:[0,0,1] neg_hi:[0,0,1]
	v_pk_fma_f32 v[14:15], v[14:15], v[66:67], v[46:47] op_sel_hi:[1,0,1] neg_lo:[0,0,1] neg_hi:[0,0,1]
	v_pk_fma_f32 v[20:21], v[20:21], v[66:67], v[52:53] op_sel_hi:[1,0,1] neg_lo:[0,0,1] neg_hi:[0,0,1]
	v_pk_fma_f32 v[18:19], v[18:19], v[66:67], v[50:51] op_sel_hi:[1,0,1] neg_lo:[0,0,1] neg_hi:[0,0,1]
	v_pk_fma_f32 v[24:25], v[24:25], v[66:67], v[56:57] op_sel_hi:[1,0,1] neg_lo:[0,0,1] neg_hi:[0,0,1]
	v_pk_fma_f32 v[22:23], v[22:23], v[66:67], v[54:55] op_sel_hi:[1,0,1] neg_lo:[0,0,1] neg_hi:[0,0,1]
	v_pk_fma_f32 v[28:29], v[28:29], v[66:67], v[60:61] op_sel_hi:[1,0,1] neg_lo:[0,0,1] neg_hi:[0,0,1]
	v_pk_fma_f32 v[26:27], v[26:27], v[66:67], v[58:59] op_sel_hi:[1,0,1] neg_lo:[0,0,1] neg_hi:[0,0,1]
	v_add_f32_e32 v66, v76, v77
	v_add_f32_e32 v36, v36, v66
	v_pk_mul_f32 v[6:7], v[38:39], v[38:39]
	v_add_f32_e32 v36, v37, v36
	v_add_f32_e32 v6, v6, v36
	v_pk_mul_f32 v[40:41], v[8:9], v[8:9]
	v_add_f32_e32 v6, v7, v6
	v_add_f32_e32 v6, v40, v6
	v_pk_mul_f32 v[42:43], v[10:11], v[10:11]
	v_add_f32_e32 v6, v41, v6
	v_add_f32_e32 v6, v42, v6
	v_pk_mul_f32 v[44:45], v[12:13], v[12:13]
	v_add_f32_e32 v6, v43, v6
	v_add_f32_e32 v6, v44, v6
	v_pk_mul_f32 v[46:47], v[14:15], v[14:15]
	v_add_f32_e32 v6, v45, v6
	v_add_f32_e32 v6, v46, v6
	v_pk_mul_f32 v[48:49], v[16:17], v[16:17]
	v_add_f32_e32 v6, v47, v6
	v_add_f32_e32 v6, v48, v6
	v_pk_mul_f32 v[50:51], v[18:19], v[18:19]
	v_add_f32_e32 v6, v49, v6
	v_add_f32_e32 v6, v50, v6
	v_pk_mul_f32 v[52:53], v[20:21], v[20:21]
	v_add_f32_e32 v6, v51, v6
	v_add_f32_e32 v6, v52, v6
	v_pk_mul_f32 v[54:55], v[22:23], v[22:23]
	v_add_f32_e32 v6, v53, v6
	v_add_f32_e32 v6, v54, v6
	v_pk_mul_f32 v[56:57], v[24:25], v[24:25]
	v_add_f32_e32 v6, v55, v6
	v_add_f32_e32 v6, v56, v6
	v_pk_mul_f32 v[58:59], v[26:27], v[26:27]
	v_add_f32_e32 v6, v57, v6
	v_add_f32_e32 v6, v58, v6
	v_pk_mul_f32 v[60:61], v[28:29], v[28:29]
	v_add_f32_e32 v6, v59, v6
	v_add_f32_e32 v6, v60, v6
	v_pk_mul_f32 v[70:71], v[30:31], v[30:31]
	v_add_f32_e32 v6, v61, v6
	v_add_f32_e32 v6, v70, v6
	v_pk_mul_f32 v[72:73], v[32:33], v[32:33]
	v_add_f32_e32 v6, v71, v6
	v_add_f32_e32 v6, v72, v6
	v_add_f32_e32 v6, v73, v6
	ds_bpermute_b32 v7, v229, v6
	v_lshl_add_u64 v[74:75], v[74:75], 0, v[214:215]
	v_lshl_add_u64 v[2:3], v[74:75], 0, s[10:11]
	s_waitcnt lgkmcnt(0)
	v_add_f32_e32 v6, v6, v7
	v_fmamk_f32 v6, v6, 0x3c800000, v192
	v_cmp_gt_f32_e32 vcc, s70, v6
	v_mul_f32_e32 v7, 0x4b800000, v6
	s_nop 0
	v_cndmask_b32_e32 v6, v6, v7, vcc
	v_rsq_f32_e32 v6, v6
	s_nop 0
	v_mul_f32_e32 v7, 0x45800000, v6
	v_cndmask_b32_e32 v6, v6, v7, vcc
	v_mul_f32_e32 v36, v233, v6
	v_pk_mul_f32 v[6:7], v[34:35], v[36:37] op_sel_hi:[1,0]
	v_pk_mul_f32 v[4:5], v[4:5], v[36:37] op_sel_hi:[1,0]
	s_waitcnt vmcnt(0)
	v_pk_mul_f32 v[6:7], v[62:63], v[6:7]
	v_pk_mul_f32 v[4:5], v[64:65], v[4:5]
	v_cvt_pk_bf16_f32 v6, v6, v7
	v_cvt_pk_bf16_f32 v7, v4, v5
	v_add_co_u32_e32 v4, vcc, s2, v74
	v_pk_mul_f32 v[34:35], v[38:39], v[36:37] op_sel_hi:[1,0]
	s_nop 0
	v_addc_co_u32_e32 v5, vcc, 0, v75, vcc
	global_store_dwordx2 v[4:5], v[6:7], off offset:1024
	v_pk_mul_f32 v[8:9], v[8:9], v[36:37] op_sel_hi:[1,0]
	v_mov_b64_e32 v[4:5], v[98:99]
	v_mov_b64_e32 v[6:7], v[100:101]
	v_pk_mul_f32 v[4:5], v[4:5], v[34:35]
	v_pk_mul_f32 v[6:7], v[6:7], v[8:9]
	v_cvt_pk_bf16_f32 v4, v4, v5
	v_cvt_pk_bf16_f32 v5, v6, v7
	global_store_dwordx2 v[2:3], v[4:5], off offset:16
	v_pk_mul_f32 v[8:9], v[10:11], v[36:37] op_sel_hi:[1,0]
	v_mov_b64_e32 v[4:5], v[102:103]
	v_mov_b64_e32 v[6:7], v[104:105]
	v_pk_mul_f32 v[4:5], v[4:5], v[8:9]
	v_pk_mul_f32 v[8:9], v[12:13], v[36:37] op_sel_hi:[1,0]
	v_cvt_pk_bf16_f32 v4, v4, v5
	v_pk_mul_f32 v[6:7], v[6:7], v[8:9]
	v_pk_mul_f32 v[8:9], v[14:15], v[36:37] op_sel_hi:[1,0]
	v_cvt_pk_bf16_f32 v5, v6, v7
	global_store_dwordx2 v[2:3], v[4:5], off offset:32
	v_mov_b64_e32 v[4:5], v[106:107]
	v_mov_b64_e32 v[6:7], v[108:109]
	v_pk_mul_f32 v[4:5], v[4:5], v[8:9]
	v_pk_mul_f32 v[8:9], v[16:17], v[36:37] op_sel_hi:[1,0]
	v_cvt_pk_bf16_f32 v4, v4, v5
	v_pk_mul_f32 v[6:7], v[6:7], v[8:9]
	v_pk_mul_f32 v[8:9], v[18:19], v[36:37] op_sel_hi:[1,0]
	v_cvt_pk_bf16_f32 v5, v6, v7
	global_store_dwordx2 v[2:3], v[4:5], off offset:48
	v_mov_b64_e32 v[4:5], v[110:111]
	v_mov_b64_e32 v[6:7], v[112:113]
	v_pk_mul_f32 v[4:5], v[4:5], v[8:9]
	v_pk_mul_f32 v[8:9], v[20:21], v[36:37] op_sel_hi:[1,0]
	v_cvt_pk_bf16_f32 v4, v4, v5
	v_pk_mul_f32 v[6:7], v[6:7], v[8:9]
	v_pk_mul_f32 v[8:9], v[22:23], v[36:37] op_sel_hi:[1,0]
	v_cvt_pk_bf16_f32 v5, v6, v7
	global_store_dwordx2 v[2:3], v[4:5], off offset:64
	v_mov_b64_e32 v[4:5], v[114:115]
	v_mov_b64_e32 v[6:7], v[116:117]
	v_pk_mul_f32 v[4:5], v[4:5], v[8:9]
	v_pk_mul_f32 v[8:9], v[24:25], v[36:37] op_sel_hi:[1,0]
	v_cvt_pk_bf16_f32 v4, v4, v5
	v_pk_mul_f32 v[6:7], v[6:7], v[8:9]
	v_pk_mul_f32 v[8:9], v[26:27], v[36:37] op_sel_hi:[1,0]
	v_cvt_pk_bf16_f32 v5, v6, v7
	global_store_dwordx2 v[2:3], v[4:5], off offset:80
	v_mov_b64_e32 v[4:5], v[122:123]
	v_mov_b64_e32 v[6:7], v[124:125]
	v_pk_mul_f32 v[4:5], v[4:5], v[8:9]
	v_pk_mul_f32 v[8:9], v[28:29], v[36:37] op_sel_hi:[1,0]
	v_cvt_pk_bf16_f32 v4, v4, v5
	v_pk_mul_f32 v[6:7], v[6:7], v[8:9]
	v_pk_mul_f32 v[8:9], v[30:31], v[36:37] op_sel_hi:[1,0]
	v_cvt_pk_bf16_f32 v5, v6, v7
	global_store_dwordx2 v[2:3], v[4:5], off offset:96
	v_mov_b64_e32 v[4:5], v[126:127]
	v_mov_b64_e32 v[6:7], v[128:129]
	v_pk_mul_f32 v[4:5], v[4:5], v[8:9]
	v_pk_mul_f32 v[8:9], v[32:33], v[36:37] op_sel_hi:[1,0]
	v_cvt_pk_bf16_f32 v4, v4, v5
	v_pk_mul_f32 v[6:7], v[6:7], v[8:9]
	s_nop 0
	v_cvt_pk_bf16_f32 v5, v6, v7
	global_store_dwordx2 v[2:3], v[4:5], off offset:112
	s_cbranch_scc0 .LBB0_745
